# phase-1 RoPE epilogue: cos/sin table rows prefetched four iterations ahead into free registers v202-v233, counted vmcnt waits
# baseline (speedup 1.0000x reference)
; __device__ __forceinline__ unsigned cvt_pk_bf16(float lo, float hi) { unsigned r; asm volatile("v_cvt_pk_bf16_f32 %0, %1, %2" : "=v"(r) : "v"(lo), "v"(hi)); return r; }
;     __device__ __forceinline__ void operator()(const f32x4 (&acc)[2][2][4][2], const Unit& u, int wr, int wc, int fr, int fq) const {
;     ...
;             if (kind == 0) {
;                 const int g4 = 4 * (((cl & 63) >> 3));
;                 bf16_t* dst = (bf16_t*)(ws + off) + ((size_t)hidx * 4096 + pos0) * 64 + g4;
;                 const f32x2v* tab = (const f32x2v*)(ws + off_rope) + (size_t)pos0 * 32 + g4;
; #pragma unroll
;                 for (int ai = 0; ai < 2; ++ai)
; #pragma unroll
;                     for (int m = 0; m < 4; ++m) {
;                         const int dp = ai * HALF + m * 16;
;                         const f32x4 x1 = acc[ai][bj][m][0], x2 = acc[ai][bj][m][1];
;                         const f32x4 t01 = *(const f32x4*)(tab + (size_t)dp * 32), t23 = *(const f32x4*)(tab + (size_t)dp * 32 + 2);
;                         const float c0 = t01[0], s0 = t01[1], c1 = t01[2], s1 = t01[3], c2 = t23[0], s2 = t23[1], c3 = t23[2], s3 = t23[3];
;                         u32x2v lo, hi;
;                         lo.x = cvt_pk_bf16(x1[0] * c0 - x2[0] * s0, x1[1] * c1 - x2[1] * s1); lo.y = cvt_pk_bf16(x1[2] * c2 - x2[2] * s2, x1[3] * c3 - x2[3] * s3);
;                         hi.x = cvt_pk_bf16(x1[0] * s0 + x2[0] * c0, x1[1] * s1 + x2[1] * c1); hi.y = cvt_pk_bf16(x1[2] * s2 + x2[2] * c2, x1[3] * s3 + x2[3] * c3);
;                         *(u32x2v*)(dst + (size_t)dp * 64) = lo; *(u32x2v*)(dst + (size_t)dp * 64 + 32) = hi;
;                     }
.LBB0_237:
	v_lshlrev_b32_e32 v160, 8, v181
	v_mov_b32_e32 v161, v139
	v_lshl_add_u64 v[164:165], v[150:151], 0, v[160:161]
	v_lshlrev_b32_e32 v138, 7, v181
	s_andn2_b64 vcc, exec, s[44:45]
	v_lshlrev_b32_e32 v176, 1, v144
	v_lshl_add_u64 v[174:175], v[164:165], 0, s[12:13]
	v_lshl_add_u64 v[172:173], v[164:165], 0, s[14:15]
	v_lshl_add_u64 v[170:171], v[164:165], 0, s[16:17]
	v_lshl_add_u64 v[168:169], v[164:165], 0, s[18:19]
	v_lshl_add_u64 v[166:167], v[164:165], 0, s[20:21]
	v_lshl_add_u64 v[162:163], v[164:165], 0, s[22:23]
	v_lshl_add_u64 v[160:161], v[164:165], 0, s[24:25]
	s_cbranch_vccnz .LBB0_239
	global_load_dwordx4 v[202:205], v[164:165], off
	global_load_dwordx4 v[206:209], v[164:165], off offset:16
	global_load_dwordx4 v[210:213], v[174:175], off
	global_load_dwordx4 v[214:217], v[174:175], off offset:16
	global_load_dwordx4 v[218:221], v[172:173], off
	global_load_dwordx4 v[222:225], v[172:173], off offset:16
	global_load_dwordx4 v[226:229], v[170:171], off
	global_load_dwordx4 v[230:233], v[170:171], off offset:16
	s_add_u32 s36, s88, s36
	s_addc_u32 s37, s89, s37
	s_ashr_i32 s39, s38, 31
	s_lshl_b64 s[2:3], s[38:39], 19
	s_add_u32 s2, s36, s2
	v_mov_b32_e32 v190, v122
	v_mov_b32_e32 v191, v126
	v_mov_b32_e32 v192, v123
	v_mov_b32_e32 v193, v127
	v_mov_b32_e32 v194, v124
	v_mov_b32_e32 v195, v128
	v_mov_b32_e32 v196, v125
	v_mov_b32_e32 v197, v129
	v_mov_b32_e32 v198, v126
	v_mov_b32_e32 v199, v122
	v_mov_b32_e32 v122, v127
	v_mov_b32_e32 v201, v124
	v_mov_b32_e32 v124, v129
	s_addc_u32 s3, s37, s3
	v_mov_b32_e32 v177, v139
	v_mov_b32_e32 v200, v128
	v_lshl_add_u64 v[126:127], s[2:3], 0, v[138:139]
	v_add_co_u32_e32 v128, vcc, s57, v164
	v_lshl_add_u64 v[126:127], v[126:127], 0, v[176:177]
	s_nop 0
	v_addc_co_u32_e32 v129, vcc, 0, v165, vcc
	s_waitcnt vmcnt(6)
	v_pk_mul_f32 v[190:191], v[190:191], v[202:203]
	v_pk_mul_f32 v[192:193], v[192:193], v[204:205]
	v_pk_mul_f32 v[194:195], v[194:195], v[206:207]
	v_pk_mul_f32 v[196:197], v[196:197], v[208:209]
	v_pk_mul_f32 v[182:183], v[198:199], v[202:203]
	v_pk_mul_f32 v[122:123], v[122:123], v[204:205]
	v_pk_mul_f32 v[124:125], v[124:125], v[208:209]
	v_pk_mul_f32 v[184:185], v[200:201], v[206:207]
	global_load_dwordx4 v[202:205], v[168:169], off
	global_load_dwordx4 v[206:209], v[168:169], off offset:16
	v_sub_f32_e32 v177, v190, v191
	v_sub_f32_e32 v186, v192, v193
	v_sub_f32_e32 v187, v194, v195
	v_sub_f32_e32 v188, v196, v197
	v_add_f32_e32 v182, v183, v182
	v_add_f32_e32 v183, v123, v122
	v_add_f32_e32 v125, v125, v124
	v_cvt_pk_bf16_f32 v122, v177, v186
	v_cvt_pk_bf16_f32 v123, v187, v188
	v_add_f32_e32 v184, v185, v184
	v_cvt_pk_bf16_f32 v124, v182, v183
	v_cvt_pk_bf16_f32 v125, v184, v125
	global_store_dwordx2 v[126:127], v[122:123], off
	global_store_dwordx2 v[126:127], v[124:125], off offset:64
	v_mov_b32_e32 v186, v114
	v_mov_b32_e32 v187, v118
	v_mov_b32_e32 v188, v115
	v_mov_b32_e32 v189, v119
	v_mov_b32_e32 v190, v116
	v_mov_b32_e32 v191, v120
	v_mov_b32_e32 v192, v117
	v_mov_b32_e32 v193, v121
	v_mov_b32_e32 v194, v118
	v_mov_b32_e32 v195, v114
	v_mov_b32_e32 v114, v119
	v_mov_b32_e32 v119, v116
	v_mov_b32_e32 v116, v121
	v_mov_b32_e32 v118, v120
	s_waitcnt vmcnt(8)
	v_pk_mul_f32 v[120:121], v[186:187], v[210:211]
	v_pk_mul_f32 v[186:187], v[188:189], v[212:213]
	v_pk_mul_f32 v[188:189], v[190:191], v[214:215]
	v_pk_mul_f32 v[190:191], v[192:193], v[216:217]
	v_pk_mul_f32 v[122:123], v[194:195], v[210:211]
	v_pk_mul_f32 v[114:115], v[114:115], v[212:213]
	v_pk_mul_f32 v[116:117], v[116:117], v[216:217]
	v_pk_mul_f32 v[118:119], v[118:119], v[214:215]
	global_load_dwordx4 v[210:213], v[166:167], off
	global_load_dwordx4 v[214:217], v[166:167], off offset:16
	v_sub_f32_e32 v120, v120, v121
	v_sub_f32_e32 v121, v186, v187
	v_sub_f32_e32 v124, v188, v189
	v_sub_f32_e32 v125, v190, v191
	v_add_f32_e32 v122, v123, v122
	v_add_f32_e32 v123, v115, v114
	v_add_f32_e32 v117, v117, v116
	v_cvt_pk_bf16_f32 v114, v120, v121
	v_cvt_pk_bf16_f32 v115, v124, v125
	v_add_f32_e32 v118, v119, v118
	v_cvt_pk_bf16_f32 v116, v122, v123
	v_cvt_pk_bf16_f32 v117, v118, v117
	global_store_dwordx2 v[126:127], v[114:115], off offset:2048
	global_store_dwordx2 v[126:127], v[116:117], off offset:2112
	v_mov_b32_e32 v123, v110
	v_mov_b32_e32 v129, v112
	v_mov_b32_e32 v184, v110
	v_mov_b32_e32 v110, v112
	v_add_co_u32_e32 v112, vcc, s74, v164
	v_mov_b32_e32 v122, v106
	v_mov_b32_e32 v124, v107
	v_mov_b32_e32 v125, v111
	v_mov_b32_e32 v128, v108
	v_mov_b32_e32 v182, v109
	v_mov_b32_e32 v183, v113
	v_mov_b32_e32 v185, v106
	v_mov_b32_e32 v106, v111
	v_mov_b32_e32 v111, v108
	v_mov_b32_e32 v108, v113
	v_addc_co_u32_e32 v113, vcc, 0, v165, vcc
	v_add_co_u32_e32 v186, vcc, s73, v126
	s_waitcnt vmcnt(10)
	v_pk_mul_f32 v[122:123], v[122:123], v[218:219]
	v_pk_mul_f32 v[124:125], v[124:125], v[220:221]
	v_pk_mul_f32 v[128:129], v[128:129], v[222:223]
	v_pk_mul_f32 v[182:183], v[182:183], v[224:225]
	v_pk_mul_f32 v[114:115], v[184:185], v[218:219]
	v_pk_mul_f32 v[106:107], v[106:107], v[220:221]
	v_pk_mul_f32 v[108:109], v[108:109], v[224:225]
	v_addc_co_u32_e32 v187, vcc, 0, v127, vcc
	v_pk_mul_f32 v[110:111], v[110:111], v[222:223]
	global_load_dwordx4 v[218:221], v[162:163], off
	global_load_dwordx4 v[222:225], v[162:163], off offset:16
	v_sub_f32_e32 v116, v122, v123
	v_sub_f32_e32 v117, v124, v125
	v_sub_f32_e32 v118, v128, v129
	v_sub_f32_e32 v119, v182, v183
	v_add_f32_e32 v114, v115, v114
	v_add_f32_e32 v115, v107, v106
	v_add_f32_e32 v109, v109, v108
	v_cvt_pk_bf16_f32 v106, v116, v117
	v_cvt_pk_bf16_f32 v107, v118, v119
	v_add_f32_e32 v110, v111, v110
	v_cvt_pk_bf16_f32 v108, v114, v115
	v_cvt_pk_bf16_f32 v109, v110, v109
	global_store_dwordx2 v[186:187], v[106:107], off
	global_store_dwordx2 v[186:187], v[108:109], off offset:64
	v_mov_b32_e32 v114, v98
	v_mov_b32_e32 v115, v102
	v_mov_b32_e32 v116, v99
	v_mov_b32_e32 v117, v103
	v_mov_b32_e32 v118, v100
	v_mov_b32_e32 v119, v104
	v_mov_b32_e32 v120, v101
	v_mov_b32_e32 v121, v105
	v_mov_b32_e32 v122, v102
	v_mov_b32_e32 v123, v98
	v_mov_b32_e32 v98, v103
	v_mov_b32_e32 v103, v100
	v_mov_b32_e32 v100, v105
	v_mov_b32_e32 v102, v104
	v_add_co_u32_e32 v124, vcc, s75, v164
	s_waitcnt vmcnt(12)
; __device__ __forceinline__ unsigned cvt_pk_bf16(float lo, float hi) { unsigned r; asm volatile("v_cvt_pk_bf16_f32 %0, %1, %2" : "=v"(r) : "v"(lo), "v"(hi)); return r; }
;     __device__ __forceinline__ void operator()(const f32x4 (&acc)[2][2][4][2], const Unit& u, int wr, int wc, int fr, int fq) const {
;     ...
;             if (kind == 0) {
;                 const int g4 = 4 * (((cl & 63) >> 3));
;                 bf16_t* dst = (bf16_t*)(ws + off) + ((size_t)hidx * 4096 + pos0) * 64 + g4;
;                 const f32x2v* tab = (const f32x2v*)(ws + off_rope) + (size_t)pos0 * 32 + g4;
; #pragma unroll
;                 for (int ai = 0; ai < 2; ++ai)
; #pragma unroll
;                     for (int m = 0; m < 4; ++m) {
;                         const int dp = ai * HALF + m * 16;
;                         const f32x4 x1 = acc[ai][bj][m][0], x2 = acc[ai][bj][m][1];
;                         const f32x4 t01 = *(const f32x4*)(tab + (size_t)dp * 32), t23 = *(const f32x4*)(tab + (size_t)dp * 32 + 2);
;                         const float c0 = t01[0], s0 = t01[1], c1 = t01[2], s1 = t01[3], c2 = t23[0], s2 = t23[1], c3 = t23[2], s3 = t23[3];
;                         u32x2v lo, hi;
;                         lo.x = cvt_pk_bf16(x1[0] * c0 - x2[0] * s0, x1[1] * c1 - x2[1] * s1); lo.y = cvt_pk_bf16(x1[2] * c2 - x2[2] * s2, x1[3] * c3 - x2[3] * s3);
;                         hi.x = cvt_pk_bf16(x1[0] * s0 + x2[0] * c0, x1[1] * s1 + x2[1] * c1); hi.y = cvt_pk_bf16(x1[2] * s2 + x2[2] * c2, x1[3] * s3 + x2[3] * c3);
;                         *(u32x2v*)(dst + (size_t)dp * 64) = lo; *(u32x2v*)(dst + (size_t)dp * 64 + 32) = hi;
;                     }
	v_pk_mul_f32 v[104:105], v[114:115], v[226:227]
	v_pk_mul_f32 v[114:115], v[116:117], v[228:229]
	v_pk_mul_f32 v[116:117], v[118:119], v[230:231]
	v_pk_mul_f32 v[118:119], v[120:121], v[232:233]
	v_pk_mul_f32 v[106:107], v[122:123], v[226:227]
	v_pk_mul_f32 v[98:99], v[98:99], v[228:229]
	v_pk_mul_f32 v[100:101], v[100:101], v[232:233]
	v_pk_mul_f32 v[102:103], v[102:103], v[230:231]
	global_load_dwordx4 v[226:229], v[160:161], off
	global_load_dwordx4 v[230:233], v[160:161], off offset:16
	v_sub_f32_e32 v104, v104, v105
	v_sub_f32_e32 v105, v114, v115
	v_sub_f32_e32 v108, v116, v117
	v_sub_f32_e32 v109, v118, v119
	v_add_f32_e32 v106, v107, v106
	v_add_f32_e32 v107, v99, v98
	v_add_f32_e32 v101, v101, v100
	v_cvt_pk_bf16_f32 v98, v104, v105
	v_cvt_pk_bf16_f32 v99, v108, v109
	v_addc_co_u32_e32 v125, vcc, 0, v165, vcc
	v_add_f32_e32 v102, v103, v102
	v_cvt_pk_bf16_f32 v100, v106, v107
	v_cvt_pk_bf16_f32 v101, v102, v101
	global_store_dwordx2 v[186:187], v[98:99], off offset:2048
	global_store_dwordx2 v[186:187], v[100:101], off offset:2112
	v_add_co_u32_e32 v116, vcc, s59, v126
	v_mov_b32_e32 v106, v90
	v_mov_b32_e32 v107, v94
	v_mov_b32_e32 v108, v91
	v_mov_b32_e32 v109, v95
	v_mov_b32_e32 v110, v92
	v_mov_b32_e32 v111, v96
	v_mov_b32_e32 v112, v93
	v_mov_b32_e32 v113, v97
	v_mov_b32_e32 v114, v94
	v_mov_b32_e32 v115, v90
	v_mov_b32_e32 v90, v95
	v_mov_b32_e32 v95, v92
	v_mov_b32_e32 v92, v97
	v_addc_co_u32_e32 v117, vcc, 0, v127, vcc
	v_mov_b32_e32 v94, v96
	v_add_co_u32_e32 v118, vcc, s76, v126
	s_waitcnt vmcnt(14)
	v_pk_mul_f32 v[96:97], v[106:107], v[202:203]
	v_pk_mul_f32 v[106:107], v[108:109], v[204:205]
	v_pk_mul_f32 v[108:109], v[110:111], v[206:207]
	v_pk_mul_f32 v[110:111], v[112:113], v[208:209]
	v_pk_mul_f32 v[98:99], v[114:115], v[202:203]
	v_pk_mul_f32 v[90:91], v[90:91], v[204:205]
	v_pk_mul_f32 v[92:93], v[92:93], v[208:209]
	v_addc_co_u32_e32 v119, vcc, 0, v127, vcc
	v_pk_mul_f32 v[94:95], v[94:95], v[206:207]
	v_sub_f32_e32 v96, v96, v97
	v_sub_f32_e32 v97, v106, v107
	v_sub_f32_e32 v100, v108, v109
	v_sub_f32_e32 v101, v110, v111
	v_add_f32_e32 v98, v99, v98
	v_add_f32_e32 v99, v91, v90
	v_add_f32_e32 v93, v93, v92
	v_cvt_pk_bf16_f32 v90, v96, v97
	v_cvt_pk_bf16_f32 v91, v100, v101
	v_add_f32_e32 v94, v95, v94
	v_cvt_pk_bf16_f32 v92, v98, v99
	v_cvt_pk_bf16_f32 v93, v94, v93
	global_store_dwordx2 v[118:119], v[90:91], off offset:-4096
	global_store_dwordx2 v[116:117], v[92:93], off offset:64
	v_mov_b32_e32 v98, v82
	v_mov_b32_e32 v99, v86
	v_mov_b32_e32 v100, v83
	v_mov_b32_e32 v101, v87
	v_mov_b32_e32 v102, v84
	v_mov_b32_e32 v103, v88
	v_mov_b32_e32 v104, v85
	v_mov_b32_e32 v105, v89
	v_mov_b32_e32 v106, v86
	v_mov_b32_e32 v107, v82
	v_mov_b32_e32 v82, v87
	v_mov_b32_e32 v87, v84
	v_mov_b32_e32 v84, v89
	v_mov_b32_e32 v86, v88
	v_add_co_u32_e32 v108, vcc, s77, v164
	s_waitcnt vmcnt(12)
	v_pk_mul_f32 v[88:89], v[98:99], v[210:211]
	v_pk_mul_f32 v[98:99], v[100:101], v[212:213]
	v_pk_mul_f32 v[100:101], v[102:103], v[214:215]
	v_pk_mul_f32 v[102:103], v[104:105], v[216:217]
	v_pk_mul_f32 v[90:91], v[106:107], v[210:211]
	v_pk_mul_f32 v[82:83], v[82:83], v[212:213]
	v_pk_mul_f32 v[84:85], v[84:85], v[216:217]
	v_pk_mul_f32 v[86:87], v[86:87], v[214:215]
	v_sub_f32_e32 v88, v88, v89
	v_sub_f32_e32 v89, v98, v99
	v_sub_f32_e32 v92, v100, v101
	v_sub_f32_e32 v93, v102, v103
	v_add_f32_e32 v90, v91, v90
	v_add_f32_e32 v91, v83, v82
	v_add_f32_e32 v85, v85, v84
	v_cvt_pk_bf16_f32 v82, v88, v89
	v_cvt_pk_bf16_f32 v83, v92, v93
	v_addc_co_u32_e32 v109, vcc, 0, v165, vcc
	v_add_f32_e32 v86, v87, v86
	v_cvt_pk_bf16_f32 v84, v90, v91
	v_cvt_pk_bf16_f32 v85, v86, v85
	global_store_dwordx2 v[116:117], v[82:83], off offset:2048
	global_store_dwordx2 v[116:117], v[84:85], off offset:2112
	v_mov_b32_e32 v90, v74
	v_mov_b32_e32 v91, v78
	v_mov_b32_e32 v92, v75
	v_mov_b32_e32 v93, v79
	v_mov_b32_e32 v94, v76
	v_mov_b32_e32 v95, v80
	v_mov_b32_e32 v96, v77
	v_mov_b32_e32 v97, v81
	v_mov_b32_e32 v98, v78
	v_mov_b32_e32 v99, v74
	v_mov_b32_e32 v74, v79
	v_mov_b32_e32 v79, v76
	v_mov_b32_e32 v76, v81
	v_mov_b32_e32 v78, v80
	s_waitcnt vmcnt(10)
	v_pk_mul_f32 v[80:81], v[90:91], v[218:219]
	v_pk_mul_f32 v[90:91], v[92:93], v[220:221]
	v_pk_mul_f32 v[92:93], v[94:95], v[222:223]
	v_pk_mul_f32 v[94:95], v[96:97], v[224:225]
	v_pk_mul_f32 v[82:83], v[98:99], v[218:219]
	v_pk_mul_f32 v[74:75], v[74:75], v[220:221]
	v_pk_mul_f32 v[76:77], v[76:77], v[224:225]
	v_pk_mul_f32 v[78:79], v[78:79], v[222:223]
	v_sub_f32_e32 v80, v80, v81
	v_sub_f32_e32 v81, v90, v91
	v_sub_f32_e32 v84, v92, v93
	v_sub_f32_e32 v85, v94, v95
	v_add_f32_e32 v82, v83, v82
	v_add_f32_e32 v83, v75, v74
	v_add_f32_e32 v77, v77, v76
	v_cvt_pk_bf16_f32 v74, v80, v81
	v_cvt_pk_bf16_f32 v75, v84, v85
	v_add_f32_e32 v78, v79, v78
	v_cvt_pk_bf16_f32 v76, v82, v83
	v_cvt_pk_bf16_f32 v77, v78, v77
	global_store_dwordx2 v[118:119], v[74:75], off
	global_store_dwordx2 v[118:119], v[76:77], off offset:64
	v_mov_b32_e32 v82, v66
	v_mov_b32_e32 v83, v70
	v_mov_b32_e32 v84, v67
	v_mov_b32_e32 v85, v71
	v_mov_b32_e32 v86, v68
	v_mov_b32_e32 v87, v72
	v_mov_b32_e32 v88, v69
	v_mov_b32_e32 v89, v73
	v_mov_b32_e32 v90, v70
	v_mov_b32_e32 v91, v66
	v_mov_b32_e32 v66, v71
	v_mov_b32_e32 v71, v68
	v_mov_b32_e32 v68, v73
	v_mov_b32_e32 v70, v72
	s_waitcnt vmcnt(8)
	v_pk_mul_f32 v[72:73], v[82:83], v[226:227]
	v_pk_mul_f32 v[82:83], v[84:85], v[228:229]
	v_pk_mul_f32 v[84:85], v[86:87], v[230:231]
	v_pk_mul_f32 v[86:87], v[88:89], v[232:233]
	v_pk_mul_f32 v[74:75], v[90:91], v[226:227]
	v_pk_mul_f32 v[66:67], v[66:67], v[228:229]
	v_pk_mul_f32 v[68:69], v[68:69], v[232:233]
	v_pk_mul_f32 v[70:71], v[70:71], v[230:231]
	v_sub_f32_e32 v72, v72, v73
	v_sub_f32_e32 v73, v82, v83
	v_sub_f32_e32 v76, v84, v85
	v_sub_f32_e32 v77, v86, v87
	v_add_f32_e32 v74, v75, v74
	v_add_f32_e32 v75, v67, v66
	v_add_f32_e32 v69, v69, v68
	v_cvt_pk_bf16_f32 v66, v72, v73
	v_cvt_pk_bf16_f32 v67, v76, v77
	v_add_f32_e32 v70, v71, v70
	v_cvt_pk_bf16_f32 v68, v74, v75
	v_cvt_pk_bf16_f32 v69, v70, v69
	global_store_dwordx2 v[118:119], v[66:67], off offset:2048
	global_store_dwordx2 v[118:119], v[68:69], off offset:2112

; __device__ __forceinline__ unsigned cvt_pk_bf16(float lo, float hi) { unsigned r; asm volatile("v_cvt_pk_bf16_f32 %0, %1, %2" : "=v"(r) : "v"(lo), "v"(hi)); return r; }
;     __device__ __forceinline__ void operator()(const f32x4 (&acc)[2][2][4][2], const Unit& u, int wr, int wc, int fr, int fq) const {
;     ...
;             if (kind == 0) {
;                 const int g4 = 4 * (((cl & 63) >> 3));
;                 bf16_t* dst = (bf16_t*)(ws + off) + ((size_t)hidx * 4096 + pos0) * 64 + g4;
;                 const f32x2v* tab = (const f32x2v*)(ws + off_rope) + (size_t)pos0 * 32 + g4;
; #pragma unroll
;                 for (int ai = 0; ai < 2; ++ai)
; #pragma unroll
;                     for (int m = 0; m < 4; ++m) {
;                         const int dp = ai * HALF + m * 16;
;                         const f32x4 x1 = acc[ai][bj][m][0], x2 = acc[ai][bj][m][1];
;                         const f32x4 t01 = *(const f32x4*)(tab + (size_t)dp * 32), t23 = *(const f32x4*)(tab + (size_t)dp * 32 + 2);
;                         const float c0 = t01[0], s0 = t01[1], c1 = t01[2], s1 = t01[3], c2 = t23[0], s2 = t23[1], c3 = t23[2], s3 = t23[3];
;                         u32x2v lo, hi;
;                         lo.x = cvt_pk_bf16(x1[0] * c0 - x2[0] * s0, x1[1] * c1 - x2[1] * s1); lo.y = cvt_pk_bf16(x1[2] * c2 - x2[2] * s2, x1[3] * c3 - x2[3] * s3);
;                         hi.x = cvt_pk_bf16(x1[0] * s0 + x2[0] * c0, x1[1] * s1 + x2[1] * c1); hi.y = cvt_pk_bf16(x1[2] * s2 + x2[2] * c2, x1[3] * s3 + x2[3] * c3);
;                         *(u32x2v*)(dst + (size_t)dp * 64) = lo; *(u32x2v*)(dst + (size_t)dp * 64 + 32) = hi;
;                     }
.LBB0_253:
	global_load_dwordx4 v[202:205], v[164:165], off
	global_load_dwordx4 v[206:209], v[164:165], off offset:16
	global_load_dwordx4 v[210:213], v[174:175], off
	global_load_dwordx4 v[214:217], v[174:175], off offset:16
	global_load_dwordx4 v[218:221], v[172:173], off
	global_load_dwordx4 v[222:225], v[172:173], off offset:16
	global_load_dwordx4 v[226:229], v[170:171], off
	global_load_dwordx4 v[230:233], v[170:171], off offset:16
	s_add_u32 s27, s88, s2
	s_addc_u32 s29, s89, s3
	s_ashr_i32 s37, s36, 31
	s_lshl_b64 s[2:3], s[36:37], 19
	s_add_u32 s2, s27, s2
	v_mov_b32_e32 v74, v58
	v_mov_b32_e32 v75, v62
	v_mov_b32_e32 v76, v59
	v_mov_b32_e32 v77, v63
	v_mov_b32_e32 v78, v60
	v_mov_b32_e32 v79, v64
	v_mov_b32_e32 v80, v61
	v_mov_b32_e32 v81, v65
	v_mov_b32_e32 v82, v62
	v_mov_b32_e32 v83, v58
	v_mov_b32_e32 v58, v63
	v_mov_b32_e32 v85, v60
	v_mov_b32_e32 v60, v65
	s_addc_u32 s3, s29, s3
	v_mov_b32_e32 v177, v139
	v_mov_b32_e32 v84, v64
	v_lshl_add_u64 v[62:63], s[2:3], 0, v[138:139]
	v_add_co_u32_e32 v86, vcc, s57, v164
	v_lshl_add_u64 v[62:63], v[62:63], 0, v[176:177]
	s_nop 0
	v_addc_co_u32_e32 v87, vcc, 0, v165, vcc
	s_waitcnt vmcnt(6)
	v_pk_mul_f32 v[64:65], v[74:75], v[202:203]
	v_pk_mul_f32 v[74:75], v[76:77], v[204:205]
	v_pk_mul_f32 v[76:77], v[78:79], v[206:207]
	v_pk_mul_f32 v[78:79], v[80:81], v[208:209]
	v_pk_mul_f32 v[66:67], v[82:83], v[202:203]
	v_pk_mul_f32 v[58:59], v[58:59], v[204:205]
	v_pk_mul_f32 v[60:61], v[60:61], v[208:209]
	v_pk_mul_f32 v[68:69], v[84:85], v[206:207]
	global_load_dwordx4 v[202:205], v[168:169], off
	global_load_dwordx4 v[206:209], v[168:169], off offset:16
	v_sub_f32_e32 v64, v64, v65
	v_sub_f32_e32 v65, v74, v75
	v_sub_f32_e32 v70, v76, v77
	v_sub_f32_e32 v71, v78, v79
	v_add_f32_e32 v66, v67, v66
	v_add_f32_e32 v67, v59, v58
	v_add_f32_e32 v61, v61, v60
	v_cvt_pk_bf16_f32 v58, v64, v65
	v_cvt_pk_bf16_f32 v59, v70, v71
	v_add_f32_e32 v68, v69, v68
	v_cvt_pk_bf16_f32 v60, v66, v67
	v_cvt_pk_bf16_f32 v61, v68, v61
	global_store_dwordx2 v[62:63], v[58:59], off
	global_store_dwordx2 v[62:63], v[60:61], off offset:64
	v_mov_b32_e32 v68, v50
	v_mov_b32_e32 v69, v54
	v_mov_b32_e32 v70, v51
	v_mov_b32_e32 v71, v55
	v_mov_b32_e32 v72, v52
	v_mov_b32_e32 v73, v56
	v_mov_b32_e32 v74, v53
	v_mov_b32_e32 v75, v57
	v_mov_b32_e32 v76, v54
	v_mov_b32_e32 v77, v50
	v_mov_b32_e32 v50, v55
	v_mov_b32_e32 v55, v52
	v_mov_b32_e32 v52, v57
	v_mov_b32_e32 v54, v56
	s_waitcnt vmcnt(8)
	v_pk_mul_f32 v[56:57], v[68:69], v[210:211]
	v_pk_mul_f32 v[68:69], v[70:71], v[212:213]
	v_pk_mul_f32 v[70:71], v[72:73], v[214:215]
	v_pk_mul_f32 v[72:73], v[74:75], v[216:217]
	v_pk_mul_f32 v[58:59], v[76:77], v[210:211]
	v_pk_mul_f32 v[50:51], v[50:51], v[212:213]
	v_pk_mul_f32 v[52:53], v[52:53], v[216:217]
	v_pk_mul_f32 v[54:55], v[54:55], v[214:215]
	global_load_dwordx4 v[210:213], v[166:167], off
	global_load_dwordx4 v[214:217], v[166:167], off offset:16
	v_sub_f32_e32 v56, v56, v57
	v_sub_f32_e32 v57, v68, v69
	v_sub_f32_e32 v60, v70, v71
	v_sub_f32_e32 v61, v72, v73
	v_add_f32_e32 v58, v59, v58
	v_add_f32_e32 v59, v51, v50
	v_add_f32_e32 v53, v53, v52
	v_cvt_pk_bf16_f32 v50, v56, v57
	v_cvt_pk_bf16_f32 v51, v60, v61
	v_add_f32_e32 v54, v55, v54
	v_cvt_pk_bf16_f32 v52, v58, v59
	v_cvt_pk_bf16_f32 v53, v54, v53
	global_store_dwordx2 v[62:63], v[50:51], off offset:2048
	global_store_dwordx2 v[62:63], v[52:53], off offset:2112
	v_mov_b32_e32 v59, v46
	v_mov_b32_e32 v65, v48
	v_mov_b32_e32 v68, v46
	v_mov_b32_e32 v46, v48
	v_add_co_u32_e32 v48, vcc, s74, v164
	v_mov_b32_e32 v58, v42
	v_mov_b32_e32 v60, v43
	v_mov_b32_e32 v61, v47
	v_mov_b32_e32 v64, v44
	v_mov_b32_e32 v66, v45
	v_mov_b32_e32 v67, v49
	v_mov_b32_e32 v69, v42
	v_mov_b32_e32 v42, v47
	v_mov_b32_e32 v47, v44
	v_mov_b32_e32 v44, v49
	v_addc_co_u32_e32 v49, vcc, 0, v165, vcc
	v_add_co_u32_e32 v70, vcc, s73, v62
	s_waitcnt vmcnt(10)
	v_pk_mul_f32 v[58:59], v[58:59], v[218:219]
	v_pk_mul_f32 v[60:61], v[60:61], v[220:221]
	v_pk_mul_f32 v[64:65], v[64:65], v[222:223]
	v_pk_mul_f32 v[66:67], v[66:67], v[224:225]
	v_pk_mul_f32 v[50:51], v[68:69], v[218:219]
	v_pk_mul_f32 v[42:43], v[42:43], v[220:221]
	v_pk_mul_f32 v[44:45], v[44:45], v[224:225]
	v_addc_co_u32_e32 v71, vcc, 0, v63, vcc
	v_pk_mul_f32 v[46:47], v[46:47], v[222:223]
	global_load_dwordx4 v[218:221], v[162:163], off
	global_load_dwordx4 v[222:225], v[162:163], off offset:16
	v_sub_f32_e32 v52, v58, v59
	v_sub_f32_e32 v53, v60, v61
	v_sub_f32_e32 v54, v64, v65
	v_sub_f32_e32 v55, v66, v67
	v_add_f32_e32 v50, v51, v50
	v_add_f32_e32 v51, v43, v42
	v_add_f32_e32 v45, v45, v44
	v_cvt_pk_bf16_f32 v42, v52, v53
	v_cvt_pk_bf16_f32 v43, v54, v55
	v_add_f32_e32 v46, v47, v46
	v_cvt_pk_bf16_f32 v44, v50, v51
	v_cvt_pk_bf16_f32 v45, v46, v45
	global_store_dwordx2 v[70:71], v[42:43], off
	global_store_dwordx2 v[70:71], v[44:45], off offset:64
	v_mov_b32_e32 v50, v34
	v_mov_b32_e32 v51, v38
	v_mov_b32_e32 v52, v35
	v_mov_b32_e32 v53, v39
	v_mov_b32_e32 v54, v36
	v_mov_b32_e32 v55, v40
	v_mov_b32_e32 v56, v37
	v_mov_b32_e32 v57, v41
	v_mov_b32_e32 v58, v38
	v_mov_b32_e32 v59, v34
	v_mov_b32_e32 v34, v39
	v_mov_b32_e32 v39, v36
	v_mov_b32_e32 v36, v41
	v_mov_b32_e32 v38, v40
	v_add_co_u32_e32 v60, vcc, s75, v164
	s_waitcnt vmcnt(12)
; __device__ __forceinline__ unsigned cvt_pk_bf16(float lo, float hi) { unsigned r; asm volatile("v_cvt_pk_bf16_f32 %0, %1, %2" : "=v"(r) : "v"(lo), "v"(hi)); return r; }
;     __device__ __forceinline__ void operator()(const f32x4 (&acc)[2][2][4][2], const Unit& u, int wr, int wc, int fr, int fq) const {
;     ...
;             if (kind == 0) {
;                 const int g4 = 4 * (((cl & 63) >> 3));
;                 bf16_t* dst = (bf16_t*)(ws + off) + ((size_t)hidx * 4096 + pos0) * 64 + g4;
;                 const f32x2v* tab = (const f32x2v*)(ws + off_rope) + (size_t)pos0 * 32 + g4;
; #pragma unroll
;                 for (int ai = 0; ai < 2; ++ai)
; #pragma unroll
;                     for (int m = 0; m < 4; ++m) {
;                         const int dp = ai * HALF + m * 16;
;                         const f32x4 x1 = acc[ai][bj][m][0], x2 = acc[ai][bj][m][1];
;                         const f32x4 t01 = *(const f32x4*)(tab + (size_t)dp * 32), t23 = *(const f32x4*)(tab + (size_t)dp * 32 + 2);
;                         const float c0 = t01[0], s0 = t01[1], c1 = t01[2], s1 = t01[3], c2 = t23[0], s2 = t23[1], c3 = t23[2], s3 = t23[3];
;                         u32x2v lo, hi;
;                         lo.x = cvt_pk_bf16(x1[0] * c0 - x2[0] * s0, x1[1] * c1 - x2[1] * s1); lo.y = cvt_pk_bf16(x1[2] * c2 - x2[2] * s2, x1[3] * c3 - x2[3] * s3);
;                         hi.x = cvt_pk_bf16(x1[0] * s0 + x2[0] * c0, x1[1] * s1 + x2[1] * c1); hi.y = cvt_pk_bf16(x1[2] * s2 + x2[2] * c2, x1[3] * s3 + x2[3] * c3);
;                         *(u32x2v*)(dst + (size_t)dp * 64) = lo; *(u32x2v*)(dst + (size_t)dp * 64 + 32) = hi;
;                     }
	v_pk_mul_f32 v[40:41], v[50:51], v[226:227]
	v_pk_mul_f32 v[50:51], v[52:53], v[228:229]
	v_pk_mul_f32 v[52:53], v[54:55], v[230:231]
	v_pk_mul_f32 v[54:55], v[56:57], v[232:233]
	v_pk_mul_f32 v[42:43], v[58:59], v[226:227]
	v_pk_mul_f32 v[34:35], v[34:35], v[228:229]
	v_pk_mul_f32 v[36:37], v[36:37], v[232:233]
	v_pk_mul_f32 v[38:39], v[38:39], v[230:231]
	global_load_dwordx4 v[226:229], v[160:161], off
	global_load_dwordx4 v[230:233], v[160:161], off offset:16
	v_sub_f32_e32 v40, v40, v41
	v_sub_f32_e32 v41, v50, v51
	v_sub_f32_e32 v44, v52, v53
	v_sub_f32_e32 v45, v54, v55
	v_add_f32_e32 v42, v43, v42
	v_add_f32_e32 v43, v35, v34
	v_add_f32_e32 v37, v37, v36
	v_cvt_pk_bf16_f32 v34, v40, v41
	v_cvt_pk_bf16_f32 v35, v44, v45
	v_addc_co_u32_e32 v61, vcc, 0, v165, vcc
	v_add_f32_e32 v38, v39, v38
	v_cvt_pk_bf16_f32 v36, v42, v43
	v_cvt_pk_bf16_f32 v37, v38, v37
	global_store_dwordx2 v[70:71], v[34:35], off offset:2048
	global_store_dwordx2 v[70:71], v[36:37], off offset:2112
	v_add_co_u32_e32 v52, vcc, s59, v62
	v_mov_b32_e32 v42, v26
	v_mov_b32_e32 v43, v30
	v_mov_b32_e32 v44, v27
	v_mov_b32_e32 v45, v31
	v_mov_b32_e32 v46, v28
	v_mov_b32_e32 v47, v32
	v_mov_b32_e32 v48, v29
	v_mov_b32_e32 v49, v33
	v_mov_b32_e32 v50, v30
	v_mov_b32_e32 v51, v26
	v_mov_b32_e32 v26, v31
	v_mov_b32_e32 v31, v28
	v_mov_b32_e32 v28, v33
	v_addc_co_u32_e32 v53, vcc, 0, v63, vcc
	v_mov_b32_e32 v30, v32
	v_add_co_u32_e32 v54, vcc, s76, v62
	s_waitcnt vmcnt(14)
	v_pk_mul_f32 v[32:33], v[42:43], v[202:203]
	v_pk_mul_f32 v[42:43], v[44:45], v[204:205]
	v_pk_mul_f32 v[44:45], v[46:47], v[206:207]
	v_pk_mul_f32 v[46:47], v[48:49], v[208:209]
	v_pk_mul_f32 v[34:35], v[50:51], v[202:203]
	v_pk_mul_f32 v[26:27], v[26:27], v[204:205]
	v_pk_mul_f32 v[28:29], v[28:29], v[208:209]
	v_addc_co_u32_e32 v55, vcc, 0, v63, vcc
	v_pk_mul_f32 v[30:31], v[30:31], v[206:207]
	v_sub_f32_e32 v32, v32, v33
	v_sub_f32_e32 v33, v42, v43
	v_sub_f32_e32 v36, v44, v45
	v_sub_f32_e32 v37, v46, v47
	v_add_f32_e32 v34, v35, v34
	v_add_f32_e32 v35, v27, v26
	v_add_f32_e32 v29, v29, v28
	v_cvt_pk_bf16_f32 v26, v32, v33
	v_cvt_pk_bf16_f32 v27, v36, v37
	v_add_f32_e32 v30, v31, v30
	v_cvt_pk_bf16_f32 v28, v34, v35
	v_cvt_pk_bf16_f32 v29, v30, v29
	global_store_dwordx2 v[54:55], v[26:27], off offset:-4096
	global_store_dwordx2 v[52:53], v[28:29], off offset:64
	v_mov_b32_e32 v34, v18
	v_mov_b32_e32 v35, v22
	v_mov_b32_e32 v36, v19
	v_mov_b32_e32 v37, v23
	v_mov_b32_e32 v38, v20
	v_mov_b32_e32 v39, v24
	v_mov_b32_e32 v40, v21
	v_mov_b32_e32 v41, v25
	v_mov_b32_e32 v42, v22
	v_mov_b32_e32 v43, v18
	v_mov_b32_e32 v18, v23
	v_mov_b32_e32 v23, v20
	v_mov_b32_e32 v20, v25
	v_mov_b32_e32 v22, v24
	v_add_co_u32_e32 v44, vcc, s77, v164
	s_waitcnt vmcnt(12)
	v_pk_mul_f32 v[24:25], v[34:35], v[210:211]
	v_pk_mul_f32 v[34:35], v[36:37], v[212:213]
	v_pk_mul_f32 v[36:37], v[38:39], v[214:215]
	v_pk_mul_f32 v[38:39], v[40:41], v[216:217]
	v_pk_mul_f32 v[26:27], v[42:43], v[210:211]
	v_pk_mul_f32 v[18:19], v[18:19], v[212:213]
	v_pk_mul_f32 v[20:21], v[20:21], v[216:217]
	v_pk_mul_f32 v[22:23], v[22:23], v[214:215]
	v_sub_f32_e32 v24, v24, v25
	v_sub_f32_e32 v25, v34, v35
	v_sub_f32_e32 v28, v36, v37
	v_sub_f32_e32 v29, v38, v39
	v_add_f32_e32 v26, v27, v26
	v_add_f32_e32 v27, v19, v18
	v_add_f32_e32 v21, v21, v20
	v_cvt_pk_bf16_f32 v18, v24, v25
	v_cvt_pk_bf16_f32 v19, v28, v29
	v_addc_co_u32_e32 v45, vcc, 0, v165, vcc
	v_add_f32_e32 v22, v23, v22
	v_cvt_pk_bf16_f32 v20, v26, v27
	v_cvt_pk_bf16_f32 v21, v22, v21
	global_store_dwordx2 v[52:53], v[18:19], off offset:2048
	global_store_dwordx2 v[52:53], v[20:21], off offset:2112
	v_mov_b32_e32 v26, v10
	v_mov_b32_e32 v27, v14
	v_mov_b32_e32 v28, v11
	v_mov_b32_e32 v29, v15
	v_mov_b32_e32 v30, v12
	v_mov_b32_e32 v31, v16
	v_mov_b32_e32 v32, v13
	v_mov_b32_e32 v33, v17
	v_mov_b32_e32 v34, v14
	v_mov_b32_e32 v35, v10
	v_mov_b32_e32 v10, v15
	v_mov_b32_e32 v15, v12
	v_mov_b32_e32 v12, v17
	v_mov_b32_e32 v14, v16
	s_waitcnt vmcnt(10)
	v_pk_mul_f32 v[16:17], v[26:27], v[218:219]
	v_pk_mul_f32 v[26:27], v[28:29], v[220:221]
	v_pk_mul_f32 v[28:29], v[30:31], v[222:223]
	v_pk_mul_f32 v[30:31], v[32:33], v[224:225]
	v_pk_mul_f32 v[18:19], v[34:35], v[218:219]
	v_pk_mul_f32 v[10:11], v[10:11], v[220:221]
	v_pk_mul_f32 v[12:13], v[12:13], v[224:225]
	v_pk_mul_f32 v[14:15], v[14:15], v[222:223]
	v_sub_f32_e32 v16, v16, v17
	v_sub_f32_e32 v17, v26, v27
	v_sub_f32_e32 v20, v28, v29
	v_sub_f32_e32 v21, v30, v31
	v_add_f32_e32 v18, v19, v18
	v_add_f32_e32 v19, v11, v10
	v_add_f32_e32 v13, v13, v12
	v_cvt_pk_bf16_f32 v10, v16, v17
	v_cvt_pk_bf16_f32 v11, v20, v21
	v_add_f32_e32 v14, v15, v14
	v_cvt_pk_bf16_f32 v12, v18, v19
	v_cvt_pk_bf16_f32 v13, v14, v13
	global_store_dwordx2 v[54:55], v[10:11], off
	global_store_dwordx2 v[54:55], v[12:13], off offset:64
	v_mov_b32_e32 v18, v6
	v_mov_b32_e32 v19, v2
	v_mov_b32_e32 v20, v7
	v_mov_b32_e32 v21, v3
	v_mov_b32_e32 v22, v8
	v_mov_b32_e32 v23, v4
	v_mov_b32_e32 v24, v9
	v_mov_b32_e32 v25, v5
	v_mov_b32_e32 v26, v2
	v_mov_b32_e32 v27, v6
	v_mov_b32_e32 v6, v3
	v_mov_b32_e32 v2, v4
	v_mov_b32_e32 v3, v8
	v_mov_b32_e32 v8, v5
	s_waitcnt vmcnt(8)
	v_pk_mul_f32 v[4:5], v[18:19], v[226:227]
	v_pk_mul_f32 v[18:19], v[20:21], v[228:229]
	v_pk_mul_f32 v[20:21], v[22:23], v[230:231]
	v_pk_mul_f32 v[22:23], v[24:25], v[232:233]
	v_pk_mul_f32 v[6:7], v[6:7], v[228:229]
	v_pk_mul_f32 v[2:3], v[2:3], v[230:231]
	v_pk_mul_f32 v[10:11], v[26:27], v[226:227]
	v_pk_mul_f32 v[8:9], v[8:9], v[232:233]
	v_sub_f32_e32 v4, v4, v5
	v_sub_f32_e32 v5, v18, v19
	v_sub_f32_e32 v12, v20, v21
	v_sub_f32_e32 v13, v22, v23
	v_add_f32_e32 v6, v7, v6
	v_add_f32_e32 v7, v3, v2
	v_cvt_pk_bf16_f32 v2, v4, v5
	v_cvt_pk_bf16_f32 v3, v12, v13
	v_add_f32_e32 v10, v11, v10
	v_add_f32_e32 v8, v9, v8
	v_cvt_pk_bf16_f32 v4, v10, v6
	v_cvt_pk_bf16_f32 v5, v7, v8
	global_store_dwordx2 v[54:55], v[2:3], off offset:2048
	global_store_dwordx2 v[54:55], v[4:5], off offset:2112
	s_andn2_b64 vcc, exec, s[0:1]
	s_mov_b64 s[0:1], -1
	s_cbranch_vccnz .LBB0_187
	s_branch .LBB0_276

;     constexpr int SB = KT_BYTES + (HAS_V ? DV * VP : 0);
;     KVStage<DV> st;
;     int jn = j0;
;     if (probe != 1) { kv_gload<DV, HAS_V>(st, Kb, VTb, ldv, jn * 64); kv_sstore<DV, HAS_V>(st, lds); }
;     __syncthreads();
;     ...
;         const bf16_t* Kw = (const bf16_t*)(p.ws + OFF_KW) + (size_t)bg * 4096 * 64;
;         const bf16_t* VwT = (const bf16_t*)(p.ws + OFF_VWT) + (size_t)bg * 64 * 4096;
;         const int tlo = (q0 > 511 ? q0 - 511 : 0) >> 6, thi = (q0 + 63) >> 6;
;         f32x16 o[2];
; #pragma unroll
;         for (int dt = 0; dt < 2; ++dt)
; #pragma unroll
;             for (int i = 0; i < 16; ++i) o[dt][i] = 0.f;
;         float m = -1e30f; f32x16 lv;
; #pragma unroll
;         for (int i = 0; i < 16; ++i) lv[i] = 0.f;
;         kv_loop<64, true>(lds, Kw, VwT, 4096, thi - tlo + 1, tlo, inc, [&](int j, const unsigned char* sb) {
.LBB0_559:
	s_or_b64 exec, exec, s[4:5]
	v_sub_u32_e32 v66, 0xdc0, v130
	s_movk_i32 s2, 0x1ff
	v_ashrrev_i32_e32 v66, 6, v66
	v_cmp_lt_i32_e32 vcc, s2, v123
	v_mov_b32_e32 v67, v173
	v_mov_b32_e32 v175, v173
	s_waitcnt vmcnt(1)
	v_cndmask_b32_e32 v114, 0, v66, vcc
	v_lshlrev_b32_e32 v66, 1, v82
	v_lshl_add_u64 v[116:117], s[96:97], 0, v[66:67]
	s_waitcnt vmcnt(0)
	v_lshl_add_u64 v[118:119], s[82:83], 0, v[66:67]
	v_lshl_add_u32 v66, v114, 6, v187
	v_ashrrev_i32_e32 v67, 31, v66
	v_lshlrev_b64 v[66:67], 7, v[66:67]
	v_ashrrev_i32_e32 v115, 31, v114
	v_lshl_add_u64 v[66:67], v[118:119], 0, v[66:67]
	v_lshlrev_b64 v[68:69], 13, v[114:115]
	v_lshl_add_u64 v[66:67], v[66:67], 0, v[172:173]
	v_lshl_add_u64 v[68:69], v[116:117], 0, v[68:69]
	v_lshl_add_u64 v[68:69], v[68:69], 0, v[174:175]
	global_load_dwordx4 v[162:165], v[66:67], off
	global_load_dwordx4 v[166:169], v[68:69], off
	v_lshrrev_b32_e32 v66, 6, v123
	v_mov_b32_e32 v98, v173
	v_mov_b32_e32 v99, v173
	v_mov_b32_e32 v100, v173
	v_mov_b32_e32 v101, v173
	v_mov_b32_e32 v102, v173
	v_mov_b32_e32 v103, v173
	v_mov_b32_e32 v104, v173
	v_mov_b32_e32 v105, v173
	v_mov_b32_e32 v106, v173
	v_mov_b32_e32 v107, v173
	v_mov_b32_e32 v108, v173
	v_mov_b32_e32 v109, v173
	v_mov_b32_e32 v110, v173
	v_mov_b32_e32 v111, v173
	v_mov_b32_e32 v112, v173
	v_mov_b32_e32 v113, v173
	v_mov_b64_e32 v[82:83], v[98:99]
	v_sub_u32_e32 v206, v66, v114
	v_mov_b64_e32 v[66:67], v[98:99]
	v_mov_b64_e32 v[84:85], v[100:101]
	v_mov_b64_e32 v[86:87], v[102:103]
	v_mov_b64_e32 v[88:89], v[104:105]
	v_mov_b64_e32 v[90:91], v[106:107]
	v_mov_b64_e32 v[92:93], v[108:109]
	v_mov_b64_e32 v[94:95], v[110:111]
	v_mov_b64_e32 v[96:97], v[112:113]
	v_cmp_lt_i32_e32 vcc, -1, v206
	v_mov_b64_e32 v[68:69], v[100:101]
	v_mov_b64_e32 v[70:71], v[102:103]
	v_mov_b64_e32 v[72:73], v[104:105]
	v_mov_b64_e32 v[74:75], v[106:107]
	v_mov_b64_e32 v[76:77], v[108:109]
	v_mov_b64_e32 v[78:79], v[110:111]
	v_mov_b64_e32 v[80:81], v[112:113]
	s_waitcnt vmcnt(1)
	ds_write_b128 v198, v[162:165]
	s_waitcnt vmcnt(0)
	ds_write2_b64 v199, v[166:167], v[168:169] offset0:128 offset1:130
	s_waitcnt lgkmcnt(0)
	s_barrier
	s_and_saveexec_b64 s[8:9], vcc
	s_cbranch_execz .LBB0_575
	v_mov_b32_e32 v80, v173
	v_mov_b32_e32 v81, v173
	v_mov_b32_e32 v66, v173
	v_mov_b32_e32 v67, v173
	v_mov_b32_e32 v68, v173
	v_mov_b32_e32 v69, v173
	v_mov_b32_e32 v70, v173
	v_mov_b32_e32 v71, v173
	v_mov_b32_e32 v72, v173
	v_mov_b32_e32 v73, v173
	v_mov_b32_e32 v74, v173
	v_mov_b32_e32 v75, v173
	v_mov_b32_e32 v76, v173
	v_mov_b32_e32 v77, v173
	v_mov_b32_e32 v78, v173
	v_mov_b32_e32 v79, v173
	v_mov_b64_e32 v[96:97], v[80:81]
	v_mov_b64_e32 v[112:113], v[80:81]
	v_lshl_add_u64 v[188:189], v[118:119], 0, v[172:173]
	v_lshl_add_u64 v[190:191], v[116:117], 0, v[174:175]
	v_or_b32_e32 v175, 31, v203
	v_add_u32_e32 v207, 0xfffffe00, v203
	v_add_u32_e32 v208, 0xfffffe1f, v203
	v_add_u32_e32 v209, 0xfffffe00, v178
	v_add_u32_e32 v210, 1, v206
	s_mov_b32 s2, 0
	v_mov_b32_e32 v211, 0xf149f2ca
	s_mov_b64 s[10:11], 0
	v_mov_b64_e32 v[94:95], v[78:79]
	v_mov_b64_e32 v[92:93], v[76:77]
	v_mov_b64_e32 v[90:91], v[74:75]
	v_mov_b64_e32 v[88:89], v[72:73]
	v_mov_b64_e32 v[86:87], v[70:71]
	v_mov_b64_e32 v[84:85], v[68:69]
	v_mov_b64_e32 v[82:83], v[66:67]
	v_mov_b64_e32 v[110:111], v[78:79]
	v_mov_b64_e32 v[108:109], v[76:77]
	v_mov_b64_e32 v[106:107], v[74:75]
	v_mov_b64_e32 v[104:105], v[72:73]
	v_mov_b64_e32 v[102:103], v[70:71]
	v_mov_b64_e32 v[100:101], v[68:69]
	v_mov_b64_e32 v[98:99], v[66:67]
	v_readfirstlane_b32 s28, v0
	v_readfirstlane_b32 s14, v114
	v_readfirstlane_b32 s12, v206
	v_readfirstlane_b32 s21, v203
	s_bfe_u32 s28, s28, 0x10008
	s_add_i32 s12, s12, 1
	s_mov_b32 s13, 0
	s_mov_b32 s18, 0
	s_movk_i32 s19, 0x4800
	s_mov_b32 s20, 0x9000

;     ...
;     for (int i = 0; i < nt; ++i) {
;         const int j = jn;
;         const bool more = (i + 1 < nt);
;         if (more) { jn = next(j); if (probe != 1) kv_gload<DV, HAS_V>(st, Kb, VTb, ldv, jn * 64); }
	s_cmp_lt_u32 s12, 2
	s_cbranch_scc1 .Lnw_p1
	s_add_i32 s15, s14, 1

; template <int DV, bool HAS_V>
; DI void kv_gload(KVStage<DV>& st, const bf16_t* __restrict__ Kb, const bf16_t* __restrict__ VTb, int ldv, int key0) {
;     const int tid = threadIdx.x;
;     st.k[0] = *(const u32x4*)(Kb + (size_t)(key0 + (tid >> 3)) * 64 + (tid & 7) * 8);
;     if (HAS_V) {
; #pragma unroll
;         for (int i = 0; i < DV / 64; ++i) { const int c = tid + 512 * i; st.v[i] = *(const u32x4*)(VTb + (size_t)(key0 >> 6) * (DV * 64) + c * 8); }
;     }
; }
	s_lshl_b32 s4, s15, 6
	v_add_u32_e32 v228, s4, v187
	v_mov_b32_e32 v229, v173
	v_lshlrev_b64 v[228:229], 7, v[228:229]
	v_lshl_add_u64 v[228:229], v[188:189], 0, v[228:229]
	global_load_dwordx4 v[162:165], v[228:229], off
	s_lshl_b32 s4, s15, 13
	s_mov_b32 s5, 0
	v_lshl_add_u64 v[230:231], v[190:191], 0, s[4:5]
	global_load_dwordx4 v[166:169], v[230:231], off

